# dynamic per-XCD attention work queue; scan WGs join after scan
# baseline (speedup 1.0000x reference)
; #define LAS __attribute__((address_space(3)))
; __global__ void __launch_bounds__(512, 2) fwd_kernel(Args a) {
;     extern __shared__ __attribute__((aligned(16))) unsigned char lds_raw[];
;     LAS unsigned char* lds = (LAS unsigned char*)lds_raw;
;     cg::grid_group grid = cg::this_grid();
;     volatile LAS unsigned* xst = (volatile LAS unsigned*)(lds + LDS_BYTES - 16);
;     if (threadIdx.x == 0) { xst[0] = 0u; xst[1] = 0u; }
;     __syncthreads();
;     const XcdBarrier xb = xcd_barrier_post((unsigned*)(a.ws + WS_BAR), xst);
_Z10fwd_kernel4Args:
	v_mov_b32_e32 v250, 0
	s_load_dwordx8 s[4:11], s[0:1], 0xc0
	s_load_dwordx2 s[54:55], s[0:1], 0xe0
	s_mov_b32 s53, s2
	s_add_u32 s2, s0, 0xe0
	s_addc_u32 s3, s1, 0
	s_waitcnt lgkmcnt(0)
	v_writelane_b32 v249, s4, 0
	v_and_b32_e32 v155, 0x3ff, v0
	s_nop 0
	v_writelane_b32 v249, s5, 1
	v_writelane_b32 v249, s6, 2
	v_writelane_b32 v249, s7, 3
	v_writelane_b32 v249, s8, 4
	v_writelane_b32 v249, s9, 5
	v_writelane_b32 v249, s10, 6
	v_writelane_b32 v249, s11, 7
	v_writelane_b32 v249, s2, 8
	v_cmp_eq_u32_e64 s[4:5], 0, v155
	s_nop 0
	v_writelane_b32 v249, s3, 9
	s_mov_b64 s[2:3], exec
	v_writelane_b32 v249, s4, 10
	s_nop 1
	v_writelane_b32 v249, s5, 11
	s_and_b64 s[4:5], s[2:3], s[4:5]
	s_mov_b64 exec, s[4:5]
	s_cbranch_execz .LBB0_2
	s_add_i32 s4, 0, 0x25ff0
	v_mov_b32_e32 v1, 0
	v_mov_b32_e32 v2, s4
	s_add_i32 s4, 0, 0x25ff4
	ds_write_b32 v2, v1
	v_mov_b32_e32 v2, s4
	ds_write_b32 v2, v1

; DI void phase_mix(const Args& a, int l, LAS unsigned char* lds) {
;     ...
;         if (gridDim.x - nscan == 128) { const int sb = blockIdx.x, xcd = sb & 7, slot = sb >> 3; attn_item(a, l, slot * 16 + 2 * xcd, lds); }
;     } else { const int na = gridDim.x - nscan;
;     ...
;         for (int it = blockIdx.x - nscan; it < 1024; it += na) attn_item(a, l, it, lds, true);
;     ...
;         if (na == 128) {
;             const int ab = blockIdx.x - nscan, xcd = ab & 7, slot = ab >> 3;
;             for (int r = 0; r < 8; ++r) {
;                 const int bg = 2 * xcd + (r >> 2), rr = r & 3;
;                 const int qb = rr == 0 ? 63 - slot : rr == 1 ? slot : rr == 2 ? 47 - slot : 16 + slot;
;                 if (r == 1) continue;
;                 attn_item(a, l, qb * 16 + bg, lds);
;             }
;         } else { for (int it = blockIdx.x - nscan; it < 1024; it += na) attn_item(a, l, it, lds); } }
.LBB0_205:
	s_and_b64 vcc, exec, s[0:1]
	s_cbranch_vccz .LBB0_775
	v_readlane_b32 s2, v245, 14
	v_readlane_b32 s3, v245, 15
	s_add_u32 s0, s2, 0x2280000
	s_addc_u32 s1, s3, 0
	v_writelane_b32 v245, s0, 48
	s_nop 1
	v_writelane_b32 v245, s1, 49
	s_add_u32 s0, s2, 0x2290000
	s_addc_u32 s1, s3, 0
	v_writelane_b32 v245, s0, 50
	s_nop 1
	v_writelane_b32 v245, s1, 51
	s_add_u32 s0, s2, 0x23c0000
	s_addc_u32 s1, s3, 0
	v_writelane_b32 v245, s0, 52
	s_nop 1
	v_writelane_b32 v245, s1, 53
	s_nop 0
	v_readlane_b32 s0, v245, 12
	s_cmp_gt_i32 s0, 1
	s_mov_b64 s[0:1], -1
	s_cbranch_scc0 .LBB0_626
	v_readlane_b32 s0, v245, 14
	v_readlane_b32 s1, v245, 15
	s_add_u32 s2, s0, 0x90000
	v_writelane_b32 v245, s2, 54
	s_addc_u32 s2, s1, 0
	s_add_u32 s0, s0, 0x10000
	v_writelane_b32 v245, s2, 55
	s_addc_u32 s1, s1, 0
	v_writelane_b32 v245, s0, 56
	s_nop 1
	v_writelane_b32 v245, s1, 57
	s_nop 0
	v_readlane_b32 s0, v245, 12
	s_cmp_gt_i32 s0, 2
	s_mov_b64 s[0:1], -1
	s_cbranch_scc0 .LBB0_594
	v_readlane_b32 s0, v245, 10
	v_readlane_b32 s1, v245, 11
	s_lshl_b32 s0, s0, 6
	s_ashr_i32 s1, s0, 31
	v_readlane_b32 s4, v247, 52
	s_lshl_b64 s[0:1], s[0:1], 2
	v_readlane_b32 s10, v247, 58
	v_readlane_b32 s11, v247, 59
	s_add_u32 s0, s10, s0
	s_addc_u32 s1, s11, s1
	v_writelane_b32 v245, s0, 60
	v_readlane_b32 s5, v247, 53
	v_readlane_b32 s6, v247, 54
	v_writelane_b32 v245, s1, 61
	v_readlane_b32 s7, v247, 55
	v_readlane_b32 s0, v245, 14
	v_readlane_b32 s1, v245, 15
	s_add_u32 s2, s0, 0x1e600000
	v_writelane_b32 v245, s2, 62
	s_addc_u32 s2, s1, 0
	s_add_u32 s0, s0, 0x1ee00000
	v_writelane_b32 v244, s0, 0
	s_addc_u32 s0, s1, 0
	v_writelane_b32 v245, s2, 63
	v_writelane_b32 v244, s0, 1
	v_readlane_b32 s0, v248, 43
	s_mul_i32 s0, s0, 0xc18000
	v_readlane_b32 s2, v245, 18
	v_readlane_b32 s3, v245, 19
	s_add_u32 s0, s2, s0
	s_addc_u32 s1, s3, 0
	v_readlane_b32 s2, v248, 8
	v_writelane_b32 v244, s0, 2
	v_readlane_b32 s3, v248, 9
	s_and_b64 vcc, exec, s[2:3]
	v_writelane_b32 v244, s1, 3
	s_mov_b64 s[0:1], -1
	v_readlane_b32 s8, v247, 56
	v_readlane_b32 s9, v247, 57
	v_readlane_b32 s12, v247, 60
	v_readlane_b32 s13, v247, 61
	v_readlane_b32 s14, v247, 62
	v_readlane_b32 s15, v247, 63
	v_readlane_b32 s16, v246, 0
	v_readlane_b32 s17, v246, 1
	v_readlane_b32 s18, v246, 2
	v_readlane_b32 s19, v246, 3
	s_cbranch_vccnz .Lq_attn
	v_readlane_b32 vcc_lo, v250, 2
	s_nop 3
	s_cmp_eq_u32 vcc_lo, 0
	s_cbranch_scc1 .LBB0_407
	v_writelane_b32 v250, 0, 2
.Lq_attn:
	v_readlane_b32 s2, v248, 11
	v_readlane_b32 s3, v248, 12
	s_and_b64 vcc, exec, s[2:3]
	v_writelane_b32 v244, s56, 46
	s_nop 1
	v_writelane_b32 v244, s57, 47
	s_cbranch_vccz .LBB0_212
	v_readlane_b32 s0, v248, 13
	v_readlane_b32 s1, v248, 14
	s_andn2_b64 vcc, exec, s[0:1]
	v_readlane_b32 s0, v248, 15
	s_nop 1
	v_writelane_b32 v244, s0, 48
	s_cbranch_vccz .LBB0_216

; DI void attn_item(const Args& a, int l, int item, LAS unsigned char* lds, bool dry = false) {
;     ...
;     for (int i = tid; i < 16384; i += 512) imp[i] = 0.f;
; DI void phase_mix(const Args& a, int l, LAS unsigned char* lds) {
;     ...
;         if (na == 128) {
;             const int ab = blockIdx.x - nscan, xcd = ab & 7, slot = ab >> 3;
;             for (int r = 0; r < 8; ++r) {
;                 const int bg = 2 * xcd + (r >> 2), rr = r & 3;
;                 const int qb = rr == 0 ? 63 - slot : rr == 1 ? slot : rr == 2 ? 47 - slot : 16 + slot;
;                 if (r == 1) continue;
;                 attn_item(a, l, qb * 16 + bg, lds);
.LBB0_308:
.LBB0_309:
	v_readfirstlane_b32 s0, v155
	s_nop 0
	s_cmp_lg_u32 s0, 0
	s_cbranch_scc1 .Lq_wait
	v_readlane_b32 s0, v245, 14
	v_readlane_b32 s1, v245, 15
	v_readlane_b32 s2, v245, 10
	v_readlane_b32 s4, v248, 43
	s_nop 3
	s_lshl_b32 s2, s2, 8
	s_lshl_b32 s4, s4, 4
	s_add_u32 s2, s2, s4
	s_add_u32 s2, s2, 0x300000
	s_add_u32 s0, s0, s2
	s_addc_u32 s1, s1, 0
	s_mov_b64 s[2:3], exec
	s_mov_b64 exec, 1
	v_mov_b32_e32 v0, 1
	global_atomic_add v0, v129, v0, s[0:1] sc0
	v_mov_b32_e32 v1, 0x25000
	s_waitcnt vmcnt(0)
	ds_write_b32 v1, v0
	s_waitcnt lgkmcnt(0)
	s_mov_b64 exec, s[2:3]
.Lq_wait:
	s_barrier
	v_mov_b32_e32 v1, 0x25000
	ds_read_b32 v0, v1
	s_waitcnt lgkmcnt(0)
	v_readfirstlane_b32 s2, v0
	s_nop 3
	s_cmp_ge_u32 s2, 0x80
	s_cbranch_scc1 .LBB0_406
	s_and_b32 s22, s2, 63
	s_sub_i32 s22, 63, s22
	s_lshr_b32 s3, s2, 6
	s_lshl_b32 s3, s3, 2
	v_writelane_b32 v244, s3, 48
	s_waitcnt vmcnt(0)
	v_mov_b32_e32 v79, v155
	s_movk_i32 s0, 0x4000
	s_nop 0
	v_cmp_gt_i32_e32 vcc, s0, v79
	s_and_saveexec_b64 s[0:1], vcc
	s_movk_i32 s4, 0x3dff
	s_cbranch_execz .LBB0_319
	v_add_u32_e32 v0, 0xfffffe00, v79
	s_waitcnt lgkmcnt(0)
	v_lshl_add_u32 v1, v79, 2, 0
	s_mov_b64 s[2:3], 0

; DI void phase_mix(const Args& a, int l, LAS unsigned char* lds) {
;     ...
;         { scan_bh2(a, l, blockIdx.x >> 1, blockIdx.x & 1, lds); }
;         if (gridDim.x - nscan == 128) { const int sb = blockIdx.x, xcd = sb & 7, slot = sb >> 3; attn_item(a, l, slot * 16 + 2 * xcd, lds); }
.LBB0_500:
	s_or_b64 exec, exec, s[0:1]
	v_readlane_b32 s0, v248, 29
	v_readlane_b32 s1, v248, 30
	s_andn2_b64 vcc, exec, s[0:1]
	s_waitcnt lgkmcnt(0)
	s_barrier
	s_cbranch_vccnz .LBB0_593
	v_writelane_b32 v250, 1, 2
	s_branch .LBB0_78

; __global__ void __launch_bounds__(512, 2) fwd_kernel(Args a) {
	.amdhsa_kernel _Z10fwd_kernel4Args
		.amdhsa_group_segment_fixed_size 0
		.amdhsa_private_segment_fixed_size 0
		.amdhsa_kernarg_size 480
		.amdhsa_user_sgpr_count 2
		.amdhsa_user_sgpr_dispatch_ptr 0
		.amdhsa_user_sgpr_queue_ptr 0
		.amdhsa_user_sgpr_kernarg_segment_ptr 1
		.amdhsa_user_sgpr_dispatch_id 0
		.amdhsa_user_sgpr_kernarg_preload_length 0
		.amdhsa_user_sgpr_kernarg_preload_offset 0
		.amdhsa_user_sgpr_private_segment_size 0
		.amdhsa_uses_dynamic_stack 0
		.amdhsa_enable_private_segment 0
		.amdhsa_system_sgpr_workgroup_id_x 1
		.amdhsa_system_sgpr_workgroup_id_y 0
		.amdhsa_system_sgpr_workgroup_id_z 0
		.amdhsa_system_sgpr_workgroup_info 0
		.amdhsa_system_vgpr_workitem_id 2
		.amdhsa_next_free_vgpr 256
		.amdhsa_next_free_sgpr 100
		.amdhsa_accum_offset 256
		.amdhsa_reserve_vcc 1
		.amdhsa_float_round_mode_32 0
		.amdhsa_float_round_mode_16_64 0
		.amdhsa_float_denorm_mode_32 3
		.amdhsa_float_denorm_mode_16_64 3
		.amdhsa_dx10_clamp 1
		.amdhsa_ieee_mode 1
		.amdhsa_fp16_overflow 0
		.amdhsa_tg_split 0
		.amdhsa_exception_fp_ieee_invalid_op 0
		.amdhsa_exception_fp_denorm_src 0
		.amdhsa_exception_fp_ieee_div_zero 0
		.amdhsa_exception_fp_ieee_overflow 0
		.amdhsa_exception_fp_ieee_underflow 0
		.amdhsa_exception_fp_ieee_inexact 0
		.amdhsa_exception_int_div_zero 0
	.end_amdhsa_kernel

; __global__ void __launch_bounds__(512, 2) fwd_kernel(Args a) {
amdhsa.kernels:
  - .agpr_count:     0
    .args:
      - .offset:         0
        .size:           224
        .value_kind:     by_value
      - .offset:         224
        .size:           4
        .value_kind:     hidden_block_count_x
      - .offset:         228
        .size:           4
        .value_kind:     hidden_block_count_y
      - .offset:         232
        .size:           4
        .value_kind:     hidden_block_count_z
      - .offset:         236
        .size:           2
        .value_kind:     hidden_group_size_x
      - .offset:         238
        .size:           2
        .value_kind:     hidden_group_size_y
      - .offset:         240
        .size:           2
        .value_kind:     hidden_group_size_z
      - .offset:         242
        .size:           2
        .value_kind:     hidden_remainder_x
      - .offset:         244
        .size:           2
        .value_kind:     hidden_remainder_y
      - .offset:         246
        .size:           2
        .value_kind:     hidden_remainder_z
      - .offset:         264
        .size:           8
        .value_kind:     hidden_global_offset_x
      - .offset:         272
        .size:           8
        .value_kind:     hidden_global_offset_y
      - .offset:         280
        .size:           8
        .value_kind:     hidden_global_offset_z
      - .offset:         288
        .size:           2
        .value_kind:     hidden_grid_dims
      - .offset:         312
        .size:           8
        .value_kind:     hidden_multigrid_sync_arg
      - .offset:         344
        .size:           4
        .value_kind:     hidden_dynamic_lds_size
    .group_segment_fixed_size: 0
    .kernarg_segment_align: 8
    .kernarg_segment_size: 480
    .language:       OpenCL C
    .language_version:
      - 2
      - 0
    .max_flat_workgroup_size: 512
    .name:           _Z10fwd_kernel4Args
    .private_segment_fixed_size: 0
    .sgpr_count:     106
    .sgpr_spill_count: 582
    .symbol:         _Z10fwd_kernel4Args.kd
    .uniform_work_group_size: 1
    .uses_dynamic_stack: false
    .vgpr_count:     256
    .vgpr_spill_count: 0
    .wavefront_size: 64
